# attention unit epilogue: 160 serialized ds_bpermute xor-shuffles replaced by DPP / v_permlane16_swap
# baseline (speedup 1.0000x reference)
; __device__ __forceinline__ void attn_unit(LAS unsigned char* lds, const bf16_t* Z, bf16_t* A2, const float* tabg, int seq_base, int S, int h, int qb, float lam) {
;     ...
;     __syncthreads();
;     if (m == 0) {
;         float ss[16];
; #pragma unroll
;         for (int r = 0; r < 16; ++r) { float q = 0.f;
; #pragma unroll
;             for (int d = 0; d < 4; ++d) { const float o = O[d][r] - X[(d * 16 + r) * 64]; O[d][r] = o; q += o * o; }
;             ss[r] = q; }
; #pragma unroll
;         for (int r = 0; r < 16; ++r) { float q = ss[r];
; #pragma unroll
;             for (int o = 1; o < 32; o <<= 1) q += __shfl_xor(q, o);
;             ss[r] = __builtin_amdgcn_rsqf(q * (1.0f / 128.0f) + RMS_EPS); }
.LBB0_313:
	s_andn2_b64 vcc, exec, s[4:5]
	s_waitcnt lgkmcnt(0)
	s_barrier
	s_cbranch_vccnz .LBB0_315
	ds_read2st64_b32 v[28:29], v69 offset0:16 offset1:17
	ds_read2st64_b32 v[30:31], v69 offset0:32 offset1:33
	ds_read2st64_b32 v[26:27], v69 offset1:1
	ds_read2st64_b32 v[32:33], v69 offset0:48 offset1:49
	ds_read2st64_b32 v[50:51], v69 offset0:54 offset1:55
	ds_read2st64_b32 v[48:49], v69 offset0:52 offset1:53
	s_waitcnt lgkmcnt(4)
	v_sub_f32_e32 v12, v12, v30
	v_sub_f32_e32 v8, v8, v31
	ds_read2st64_b32 v[30:31], v69 offset0:34 offset1:35
	s_waitcnt lgkmcnt(3)
	v_sub_f32_e32 v13, v9, v32
	v_sub_f32_e32 v6, v6, v33
	ds_read2st64_b32 v[32:33], v69 offset0:50 offset1:51
	ds_read2st64_b32 v[34:35], v69 offset0:36 offset1:37
	s_waitcnt lgkmcnt(2)
	v_sub_f32_e32 v20, v20, v30
	v_sub_f32_e32 v16, v16, v31
	ds_read2st64_b32 v[30:31], v69 offset0:4 offset1:5
	v_sub_f32_e32 v11, v11, v28
	v_sub_f32_e32 v9, v7, v27
	v_sub_f32_e32 v7, v21, v29
	ds_read2st64_b32 v[28:29], v69 offset0:18 offset1:19
	v_sub_f32_e32 v10, v10, v26
	ds_read2st64_b32 v[26:27], v69 offset0:2 offset1:3
	s_waitcnt lgkmcnt(4)
	v_sub_f32_e32 v21, v17, v32
	v_sub_f32_e32 v14, v14, v33
	s_waitcnt lgkmcnt(1)
	v_sub_f32_e32 v18, v18, v28
	ds_read2st64_b32 v[32:33], v69 offset0:20 offset1:21
	v_sub_f32_e32 v28, v89, v34
	v_sub_f32_e32 v24, v24, v35
	ds_read2st64_b32 v[34:35], v69 offset0:22 offset1:23
	v_sub_f32_e32 v25, v4, v31
	v_sub_f32_e32 v45, v38, v50
	v_sub_f32_e32 v39, v39, v51
	ds_read2st64_b32 v[50:51], v69 offset0:40 offset1:41
	v_sub_f32_e32 v22, v22, v49
	s_waitcnt lgkmcnt(1)
	v_sub_f32_e32 v31, v72, v34
	v_sub_f32_e32 v38, v42, v35
	ds_read2st64_b32 v[34:35], v69 offset0:8 offset1:9
	v_sub_f32_e32 v19, v19, v26
	v_sub_f32_e32 v17, v15, v27
	v_sub_f32_e32 v15, v92, v29
	v_sub_f32_e32 v26, v90, v32
	v_sub_f32_e32 v29, v88, v48
	v_sub_f32_e32 v23, v23, v33
	ds_read2st64_b32 v[32:33], v69 offset0:6 offset1:7
	ds_read2st64_b32 v[48:49], v69 offset0:38 offset1:39
	ds_read2st64_b32 v[82:83], v69 offset0:56 offset1:57
	v_sub_f32_e32 v27, v91, v30
	s_waitcnt lgkmcnt(3)
	v_sub_f32_e32 v36, v36, v35
	s_waitcnt lgkmcnt(2)
	v_sub_f32_e32 v30, v87, v32
	s_waitcnt lgkmcnt(1)
	v_sub_f32_e32 v32, v41, v48
	v_sub_f32_e32 v40, v40, v49
	ds_read2st64_b32 v[48:49], v69 offset0:24 offset1:25
	v_sub_f32_e32 v41, v37, v33
	v_sub_f32_e32 v37, v86, v34
	s_waitcnt lgkmcnt(1)
	v_sub_f32_e32 v44, v44, v82
	v_sub_f32_e32 v33, v76, v83
	ds_read2st64_b32 v[82:83], v69 offset0:26 offset1:27
	s_waitcnt lgkmcnt(1)
	v_sub_f32_e32 v42, v85, v48
	v_sub_f32_e32 v34, v75, v49
	v_sub_f32_e32 v35, v84, v51
	ds_read2st64_b32 v[48:49], v69 offset0:10 offset1:11
	ds_read2st64_b32 v[86:87], v69 offset0:44 offset1:45
	ds_read2st64_b32 v[84:85], v69 offset0:58 offset1:59
	v_sub_f32_e32 v43, v43, v50
	s_waitcnt lgkmcnt(3)
	v_sub_f32_e32 v50, v70, v82
	v_sub_f32_e32 v47, v47, v83
	ds_read2st64_b32 v[82:83], v69 offset0:12 offset1:13
	s_waitcnt lgkmcnt(1)
	v_sub_f32_e32 v53, v53, v84
	v_sub_f32_e32 v46, v46, v85
	ds_read2st64_b32 v[84:85], v69 offset0:28 offset1:29
	v_sub_f32_e32 v51, v71, v48
	ds_read2st64_b32 v[70:71], v69 offset0:42 offset1:43
	ds_read2st64_b32 v[88:89], v69 offset0:60 offset1:61
	s_waitcnt lgkmcnt(3)
	v_sub_f32_e32 v59, v59, v82
	v_mul_f32_e32 v80, v11, v11
	v_fmac_f32_e32 v80, v10, v10
	s_waitcnt lgkmcnt(1)
	v_sub_f32_e32 v48, v61, v71
	s_waitcnt lgkmcnt(0)
	v_sub_f32_e32 v61, v57, v88
	v_sub_f32_e32 v57, v2, v83
	ds_read2st64_b32 v[82:83], v69 offset0:14 offset1:15
	v_fmac_f32_e32 v80, v12, v12
	v_fmac_f32_e32 v80, v13, v13
	v_sub_f32_e32 v58, v58, v84
	v_sub_f32_e32 v60, v60, v86
	v_sub_f32_e32 v55, v55, v85
	v_sub_f32_e32 v56, v56, v87
	v_sub_f32_e32 v54, v54, v89
	ds_read2st64_b32 v[84:85], v69 offset0:30 offset1:31
	ds_read2st64_b32 v[86:87], v69 offset0:46 offset1:47
	ds_read2st64_b32 v[88:89], v69 offset0:62 offset1:63
	s_waitcnt lgkmcnt(3)
	v_sub_f32_e32 v62, v62, v82
	s_nop 1
	v_mov_b32_dpp v82, v80 quad_perm:[1,0,3,2] row_mask:0xf bank_mask:0xf
	v_mul_f32_e32 v77, v7, v7
	v_fmac_f32_e32 v77, v9, v9
	v_fmac_f32_e32 v77, v8, v8
	v_fmac_f32_e32 v77, v6, v6
	s_waitcnt lgkmcnt(0)
	v_add_f32_e32 v80, v80, v82
	s_nop 1
	v_mov_b32_dpp v82, v80 quad_perm:[2,3,0,1] row_mask:0xf bank_mask:0xf
	v_mul_f32_e32 v78, v18, v18
	v_fmac_f32_e32 v78, v19, v19
	v_fmac_f32_e32 v78, v20, v20
	v_fmac_f32_e32 v78, v21, v21
	s_waitcnt lgkmcnt(0)
	v_add_f32_e32 v80, v80, v82
	s_nop 1
	v_mov_b32_dpp v82, v80 row_half_mirror row_mask:0xf bank_mask:0xf
	v_mul_f32_e32 v73, v15, v15
	v_fmac_f32_e32 v73, v17, v17
	v_fmac_f32_e32 v73, v16, v16
	v_fmac_f32_e32 v73, v14, v14
	s_waitcnt lgkmcnt(0)
	v_add_f32_e32 v80, v80, v82
	s_nop 1
	v_mov_b32_dpp v82, v80 row_mirror row_mask:0xf bank_mask:0xf
	v_mul_f32_e32 v74, v26, v26
	v_fmac_f32_e32 v74, v27, v27
	v_fmac_f32_e32 v74, v28, v28
	v_fmac_f32_e32 v74, v29, v29
	s_waitcnt lgkmcnt(0)
	v_add_f32_e32 v80, v80, v82
	v_mov_b32_e32 v82, v80
	s_nop 1
	v_permlane16_swap_b32_e32 v82, v80
	v_mul_f32_e32 v4, v23, v23
	v_fmac_f32_e32 v4, v25, v25
	v_fmac_f32_e32 v4, v24, v24
	v_fmac_f32_e32 v4, v22, v22
	s_waitcnt lgkmcnt(0)
	v_add_f32_e32 v80, v80, v82
	s_nop 1
	v_mov_b32_dpp v82, v77 quad_perm:[1,0,3,2] row_mask:0xf bank_mask:0xf
	v_mul_f32_e32 v72, v31, v31
	v_fmac_f32_e32 v72, v30, v30
	v_fmac_f32_e32 v72, v32, v32
	v_fmac_f32_e32 v72, v45, v45
	s_waitcnt lgkmcnt(0)
	v_add_f32_e32 v77, v77, v82
	s_nop 1
	v_mov_b32_dpp v82, v77 quad_perm:[2,3,0,1] row_mask:0xf bank_mask:0xf
	v_mul_f32_e32 v81, v38, v38
	v_fmac_f32_e32 v81, v41, v41
	v_fmac_f32_e32 v81, v40, v40
	v_fmac_f32_e32 v81, v39, v39
	s_waitcnt lgkmcnt(0)
; __device__ __forceinline__ void attn_unit(LAS unsigned char* lds, const bf16_t* Z, bf16_t* A2, const float* tabg, int seq_base, int S, int h, int qb, float lam) {
;     ...
;         for (int r = 0; r < 16; ++r) { float q = 0.f;
; #pragma unroll
;             for (int d = 0; d < 4; ++d) { const float o = O[d][r] - X[(d * 16 + r) * 64]; O[d][r] = o; q += o * o; }
;             ss[r] = q; }
; #pragma unroll
;         for (int r = 0; r < 16; ++r) { float q = ss[r];
; #pragma unroll
;             for (int o = 1; o < 32; o <<= 1) q += __shfl_xor(q, o);
;             ss[r] = __builtin_amdgcn_rsqf(q * (1.0f / 128.0f) + RMS_EPS); }
	v_add_f32_e32 v77, v77, v82
	s_nop 1
	v_mov_b32_dpp v82, v77 row_half_mirror row_mask:0xf bank_mask:0xf
	v_mul_f32_e32 v79, v42, v42
	v_fmac_f32_e32 v79, v37, v37
	v_fmac_f32_e32 v79, v43, v43
	v_fmac_f32_e32 v79, v44, v44
	s_waitcnt lgkmcnt(0)
	v_add_f32_e32 v77, v77, v82
	s_nop 1
	v_mov_b32_dpp v82, v77 row_mirror row_mask:0xf bank_mask:0xf
	v_mul_f32_e32 v75, v34, v34
	v_fmac_f32_e32 v75, v36, v36
	v_fmac_f32_e32 v75, v35, v35
	v_fmac_f32_e32 v75, v33, v33
	s_waitcnt lgkmcnt(0)
	v_add_f32_e32 v77, v77, v82
	v_mov_b32_e32 v82, v77
	s_nop 1
	v_permlane16_swap_b32_e32 v82, v77
	v_mul_f32_e32 v76, v50, v50
	v_fmac_f32_e32 v76, v51, v51
	v_sub_f32_e32 v52, v52, v70
	v_fmac_f32_e32 v76, v52, v52
	s_waitcnt lgkmcnt(0)
	v_add_f32_e32 v77, v77, v82
	s_nop 1
	v_mov_b32_dpp v82, v78 quad_perm:[1,0,3,2] row_mask:0xf bank_mask:0xf
	v_fmac_f32_e32 v76, v53, v53
	v_sub_f32_e32 v49, v5, v49
	v_mul_f32_e32 v5, v47, v47
	v_fmac_f32_e32 v5, v49, v49
	s_waitcnt lgkmcnt(0)
	v_add_f32_e32 v78, v78, v82
	s_nop 1
	v_mov_b32_dpp v82, v78 quad_perm:[2,3,0,1] row_mask:0xf bank_mask:0xf
	v_fmac_f32_e32 v5, v48, v48
	v_fmac_f32_e32 v5, v46, v46
	v_mul_f32_e32 v71, v58, v58
	v_fmac_f32_e32 v71, v59, v59
	s_waitcnt lgkmcnt(0)
	v_add_f32_e32 v78, v78, v82
	s_nop 1
	v_mov_b32_dpp v82, v78 row_half_mirror row_mask:0xf bank_mask:0xf
	v_fmac_f32_e32 v71, v60, v60
	v_fmac_f32_e32 v71, v61, v61
	v_sub_f32_e32 v69, v68, v88
	v_sub_f32_e32 v68, v3, v83
	s_waitcnt lgkmcnt(0)
	v_add_f32_e32 v78, v78, v82
	s_nop 1
	v_mov_b32_dpp v82, v78 row_mirror row_mask:0xf bank_mask:0xf
	v_mul_f32_e32 v2, v55, v55
	v_fmac_f32_e32 v2, v57, v57
	v_fmac_f32_e32 v2, v56, v56
	v_fmac_f32_e32 v2, v54, v54
	s_waitcnt lgkmcnt(0)
	v_add_f32_e32 v78, v78, v82
	v_mov_b32_e32 v82, v78
	s_nop 1
	v_permlane16_swap_b32_e32 v82, v78
	v_sub_f32_e32 v63, v63, v84
	v_mul_f32_e32 v70, v63, v63
	v_fmac_f32_e32 v70, v62, v62
	v_sub_f32_e32 v64, v64, v86
	s_waitcnt lgkmcnt(0)
	v_add_f32_e32 v78, v78, v82
	s_nop 1
	v_mov_b32_dpp v82, v73 quad_perm:[1,0,3,2] row_mask:0xf bank_mask:0xf
	v_fmac_f32_e32 v70, v64, v64
	v_fmac_f32_e32 v70, v69, v69
	v_sub_f32_e32 v66, v66, v85
	v_mul_f32_e32 v3, v66, v66
	s_waitcnt lgkmcnt(0)
	v_add_f32_e32 v73, v73, v82
	s_nop 1
	v_mov_b32_dpp v82, v73 quad_perm:[2,3,0,1] row_mask:0xf bank_mask:0xf
	v_fmac_f32_e32 v3, v68, v68
	v_sub_f32_e32 v67, v67, v87
	v_fmac_f32_e32 v3, v67, v67
	v_sub_f32_e32 v65, v65, v89
	s_waitcnt lgkmcnt(0)
	v_add_f32_e32 v73, v73, v82
	s_nop 1
	v_mov_b32_dpp v82, v73 row_half_mirror row_mask:0xf bank_mask:0xf
	v_fmac_f32_e32 v3, v65, v65
	v_fmamk_f32 v80, v80, 0x3c000000, v244
	v_rsq_f32_e32 v80, v80
	s_lshl_b32 s4, s15, 1
	s_waitcnt lgkmcnt(0)
	v_add_f32_e32 v73, v73, v82
	s_nop 1
	v_mov_b32_dpp v82, v73 row_mirror row_mask:0xf bank_mask:0xf
	s_add_u32 s4, s6, s4
	v_ashrrev_i32_e32 v149, 31, v148
	s_addc_u32 s5, s7, 0
	v_fmamk_f32 v77, v77, 0x3c000000, v244
	s_waitcnt lgkmcnt(0)
	v_add_f32_e32 v73, v73, v82
	v_mov_b32_e32 v82, v73
	s_nop 1
	v_permlane16_swap_b32_e32 v82, v73
	v_rsq_f32_e32 v77, v77
	v_fmamk_f32 v78, v78, 0x3c000000, v244
	v_rsq_f32_e32 v78, v78
	s_waitcnt lgkmcnt(0)
	v_add_f32_e32 v73, v73, v82
	s_nop 1
	v_mov_b32_dpp v82, v74 quad_perm:[1,0,3,2] row_mask:0xf bank_mask:0xf
	v_fmamk_f32 v73, v73, 0x3c000000, v244
	v_rsq_f32_e32 v73, v73
	s_waitcnt lgkmcnt(0)
	v_add_f32_e32 v74, v74, v82
	s_nop 1
	v_mov_b32_dpp v82, v74 quad_perm:[2,3,0,1] row_mask:0xf bank_mask:0xf
	s_waitcnt lgkmcnt(0)
	v_add_f32_e32 v74, v74, v82
	s_nop 1
	v_mov_b32_dpp v82, v74 row_half_mirror row_mask:0xf bank_mask:0xf
	s_waitcnt lgkmcnt(0)
	v_add_f32_e32 v74, v74, v82
	s_nop 1
	v_mov_b32_dpp v82, v74 row_mirror row_mask:0xf bank_mask:0xf
	s_waitcnt lgkmcnt(0)
	v_add_f32_e32 v74, v74, v82
	v_mov_b32_e32 v82, v74
	s_nop 1
	v_permlane16_swap_b32_e32 v82, v74
	s_waitcnt lgkmcnt(0)
	v_add_f32_e32 v74, v74, v82
	s_nop 1
	v_mov_b32_dpp v82, v4 quad_perm:[1,0,3,2] row_mask:0xf bank_mask:0xf
	v_fmamk_f32 v74, v74, 0x3c000000, v244
	v_rsq_f32_e32 v74, v74
	s_waitcnt lgkmcnt(0)
	v_add_f32_e32 v4, v4, v82
	s_nop 1
	v_mov_b32_dpp v82, v4 quad_perm:[2,3,0,1] row_mask:0xf bank_mask:0xf
	s_waitcnt lgkmcnt(0)
	v_add_f32_e32 v4, v4, v82
	s_nop 1
	v_mov_b32_dpp v82, v4 row_half_mirror row_mask:0xf bank_mask:0xf
	s_waitcnt lgkmcnt(0)
	v_add_f32_e32 v4, v4, v82
	s_nop 1
	v_mov_b32_dpp v82, v4 row_mirror row_mask:0xf bank_mask:0xf
	s_waitcnt lgkmcnt(0)
	v_add_f32_e32 v4, v4, v82
	v_mov_b32_e32 v82, v4
	s_nop 1
	v_permlane16_swap_b32_e32 v82, v4
	s_waitcnt lgkmcnt(0)
	v_add_f32_e32 v4, v4, v82
	v_fmamk_f32 v4, v4, 0x3c000000, v244
	v_rsq_f32_e32 v82, v4
	s_nop 1
	v_mov_b32_dpp v4, v72 quad_perm:[1,0,3,2] row_mask:0xf bank_mask:0xf
	s_waitcnt lgkmcnt(0)
	v_add_f32_e32 v4, v72, v4
	s_nop 1
	v_mov_b32_dpp v72, v4 quad_perm:[2,3,0,1] row_mask:0xf bank_mask:0xf
	s_waitcnt lgkmcnt(0)
	v_add_f32_e32 v4, v4, v72
	s_nop 1
	v_mov_b32_dpp v72, v4 row_half_mirror row_mask:0xf bank_mask:0xf
	s_waitcnt lgkmcnt(0)
	v_add_f32_e32 v4, v4, v72
	s_nop 1
	v_mov_b32_dpp v72, v4 row_mirror row_mask:0xf bank_mask:0xf
	s_waitcnt lgkmcnt(0)
	v_add_f32_e32 v4, v4, v72
	v_mov_b32_e32 v72, v4
	s_nop 1
	v_permlane16_swap_b32_e32 v72, v4
	s_waitcnt lgkmcnt(0)
	v_add_f32_e32 v4, v4, v72
	v_fmamk_f32 v4, v4, 0x3c000000, v244
	v_rsq_f32_e32 v72, v4
	s_nop 1
	v_mov_b32_dpp v4, v81 quad_perm:[1,0,3,2] row_mask:0xf bank_mask:0xf
	s_waitcnt lgkmcnt(0)
	v_add_f32_e32 v4, v81, v4
	s_nop 1
	v_mov_b32_dpp v81, v4 quad_perm:[2,3,0,1] row_mask:0xf bank_mask:0xf
	s_waitcnt lgkmcnt(0)
	v_add_f32_e32 v4, v4, v81
	s_nop 1
	v_mov_b32_dpp v81, v4 row_half_mirror row_mask:0xf bank_mask:0xf
	s_waitcnt lgkmcnt(0)
; __device__ __forceinline__ void attn_unit(LAS unsigned char* lds, const bf16_t* Z, bf16_t* A2, const float* tabg, int seq_base, int S, int h, int qb, float lam) {
;     ...
;         for (int r = 0; r < 16; ++r) { float q = ss[r];
; #pragma unroll
;             for (int o = 1; o < 32; o <<= 1) q += __shfl_xor(q, o);
;             ss[r] = __builtin_amdgcn_rsqf(q * (1.0f / 128.0f) + RMS_EPS); }
	v_add_f32_e32 v4, v4, v81
	s_nop 1
	v_mov_b32_dpp v81, v4 row_mirror row_mask:0xf bank_mask:0xf
	s_waitcnt lgkmcnt(0)
	v_add_f32_e32 v4, v4, v81
	v_mov_b32_e32 v81, v4
	s_nop 1
	v_permlane16_swap_b32_e32 v81, v4
	s_waitcnt lgkmcnt(0)
	v_add_f32_e32 v4, v4, v81
	v_fmamk_f32 v4, v4, 0x3c000000, v244
	v_rsq_f32_e32 v81, v4
	s_nop 1
	v_mov_b32_dpp v4, v79 quad_perm:[1,0,3,2] row_mask:0xf bank_mask:0xf
	s_waitcnt lgkmcnt(0)
	v_add_f32_e32 v4, v79, v4
	s_nop 1
	v_mov_b32_dpp v79, v4 quad_perm:[2,3,0,1] row_mask:0xf bank_mask:0xf
	s_waitcnt lgkmcnt(0)
	v_add_f32_e32 v4, v4, v79
	s_nop 1
	v_mov_b32_dpp v79, v4 row_half_mirror row_mask:0xf bank_mask:0xf
	s_waitcnt lgkmcnt(0)
	v_add_f32_e32 v4, v4, v79
	s_nop 1
	v_mov_b32_dpp v79, v4 row_mirror row_mask:0xf bank_mask:0xf
	s_waitcnt lgkmcnt(0)
	v_add_f32_e32 v4, v4, v79
	v_mov_b32_e32 v79, v4
	s_nop 1
	v_permlane16_swap_b32_e32 v79, v4
	s_waitcnt lgkmcnt(0)
	v_add_f32_e32 v4, v4, v79
	v_fmamk_f32 v4, v4, 0x3c000000, v244
	v_rsq_f32_e32 v79, v4
	s_nop 1
	v_mov_b32_dpp v4, v75 quad_perm:[1,0,3,2] row_mask:0xf bank_mask:0xf
	s_waitcnt lgkmcnt(0)
	v_add_f32_e32 v4, v75, v4
	s_nop 1
	v_mov_b32_dpp v75, v4 quad_perm:[2,3,0,1] row_mask:0xf bank_mask:0xf
	s_waitcnt lgkmcnt(0)
	v_add_f32_e32 v4, v4, v75
	s_nop 1
	v_mov_b32_dpp v75, v4 row_half_mirror row_mask:0xf bank_mask:0xf
	s_waitcnt lgkmcnt(0)
	v_add_f32_e32 v4, v4, v75
	s_nop 1
	v_mov_b32_dpp v75, v4 row_mirror row_mask:0xf bank_mask:0xf
	s_waitcnt lgkmcnt(0)
	v_add_f32_e32 v4, v4, v75
	v_mov_b32_e32 v75, v4
	s_nop 1
	v_permlane16_swap_b32_e32 v75, v4
	s_waitcnt lgkmcnt(0)
	v_add_f32_e32 v4, v4, v75
	v_fmamk_f32 v4, v4, 0x3c000000, v244
	v_rsq_f32_e32 v75, v4
	s_nop 1
	v_mov_b32_dpp v4, v76 quad_perm:[1,0,3,2] row_mask:0xf bank_mask:0xf
	s_waitcnt lgkmcnt(0)
	v_add_f32_e32 v4, v76, v4
	s_nop 1
	v_mov_b32_dpp v76, v4 quad_perm:[2,3,0,1] row_mask:0xf bank_mask:0xf
	s_waitcnt lgkmcnt(0)
	v_add_f32_e32 v4, v4, v76
	s_nop 1
	v_mov_b32_dpp v76, v4 row_half_mirror row_mask:0xf bank_mask:0xf
	s_waitcnt lgkmcnt(0)
	v_add_f32_e32 v4, v4, v76
	s_nop 1
	v_mov_b32_dpp v76, v4 row_mirror row_mask:0xf bank_mask:0xf
	s_waitcnt lgkmcnt(0)
	v_add_f32_e32 v4, v4, v76
	v_mov_b32_e32 v76, v4
	s_nop 1
	v_permlane16_swap_b32_e32 v76, v4
	s_waitcnt lgkmcnt(0)
	v_add_f32_e32 v4, v4, v76
	v_fmamk_f32 v4, v4, 0x3c000000, v244
	v_rsq_f32_e32 v76, v4
	s_nop 1
	v_mov_b32_dpp v4, v5 quad_perm:[1,0,3,2] row_mask:0xf bank_mask:0xf
	s_waitcnt lgkmcnt(0)
	v_add_f32_e32 v4, v5, v4
	s_nop 1
	v_mov_b32_dpp v5, v4 quad_perm:[2,3,0,1] row_mask:0xf bank_mask:0xf
	s_waitcnt lgkmcnt(0)
	v_add_f32_e32 v4, v4, v5
	s_nop 1
	v_mov_b32_dpp v5, v4 row_half_mirror row_mask:0xf bank_mask:0xf
	s_waitcnt lgkmcnt(0)
	v_add_f32_e32 v4, v4, v5
	s_nop 1
	v_mov_b32_dpp v5, v4 row_mirror row_mask:0xf bank_mask:0xf
	s_waitcnt lgkmcnt(0)
	v_add_f32_e32 v4, v4, v5
	v_mov_b32_e32 v5, v4
	s_nop 1
	v_permlane16_swap_b32_e32 v5, v4
	s_waitcnt lgkmcnt(0)
	v_add_f32_e32 v4, v4, v5
	v_fmamk_f32 v4, v4, 0x3c000000, v244
	v_rsq_f32_e32 v83, v4
	s_nop 1
	v_mov_b32_dpp v4, v71 quad_perm:[1,0,3,2] row_mask:0xf bank_mask:0xf
	s_waitcnt lgkmcnt(0)
	v_add_f32_e32 v4, v71, v4
	s_nop 1
	v_mov_b32_dpp v5, v4 quad_perm:[2,3,0,1] row_mask:0xf bank_mask:0xf
	s_waitcnt lgkmcnt(0)
	v_add_f32_e32 v4, v4, v5
	s_nop 1
	v_mov_b32_dpp v5, v4 row_half_mirror row_mask:0xf bank_mask:0xf
	s_waitcnt lgkmcnt(0)
	v_add_f32_e32 v4, v4, v5
	s_nop 1
	v_mov_b32_dpp v5, v4 row_mirror row_mask:0xf bank_mask:0xf
	s_waitcnt lgkmcnt(0)
	v_add_f32_e32 v4, v4, v5
	v_mov_b32_e32 v5, v4
	s_nop 1
	v_permlane16_swap_b32_e32 v5, v4
	s_waitcnt lgkmcnt(0)
	v_add_f32_e32 v4, v4, v5
	v_fmamk_f32 v4, v4, 0x3c000000, v244
	v_rsq_f32_e32 v84, v4
	s_nop 1
	v_mov_b32_dpp v4, v2 quad_perm:[1,0,3,2] row_mask:0xf bank_mask:0xf
	s_waitcnt lgkmcnt(0)
	v_add_f32_e32 v2, v2, v4
	s_nop 1
	v_mov_b32_dpp v4, v2 quad_perm:[2,3,0,1] row_mask:0xf bank_mask:0xf
	s_waitcnt lgkmcnt(0)
	v_add_f32_e32 v2, v2, v4
	s_nop 1
	v_mov_b32_dpp v4, v2 row_half_mirror row_mask:0xf bank_mask:0xf
	s_waitcnt lgkmcnt(0)
	v_add_f32_e32 v2, v2, v4
	s_nop 1
	v_mov_b32_dpp v4, v2 row_mirror row_mask:0xf bank_mask:0xf
	s_waitcnt lgkmcnt(0)
	v_add_f32_e32 v2, v2, v4
	v_mov_b32_e32 v4, v2
	s_nop 1
	v_permlane16_swap_b32_e32 v4, v2
	s_waitcnt lgkmcnt(0)
	v_add_f32_e32 v2, v2, v4
	v_fmamk_f32 v2, v2, 0x3c000000, v244
	v_rsq_f32_e32 v85, v2
	s_nop 1
	v_mov_b32_dpp v2, v70 quad_perm:[1,0,3,2] row_mask:0xf bank_mask:0xf
	s_waitcnt lgkmcnt(0)
	v_add_f32_e32 v2, v70, v2
	s_nop 1
	v_mov_b32_dpp v4, v2 quad_perm:[2,3,0,1] row_mask:0xf bank_mask:0xf
	s_waitcnt lgkmcnt(0)
	v_add_f32_e32 v2, v2, v4
	s_nop 1
	v_mov_b32_dpp v4, v2 row_half_mirror row_mask:0xf bank_mask:0xf
	s_waitcnt lgkmcnt(0)
	v_add_f32_e32 v2, v2, v4
	s_nop 1
	v_mov_b32_dpp v4, v2 row_mirror row_mask:0xf bank_mask:0xf
	s_waitcnt lgkmcnt(0)
	v_add_f32_e32 v2, v2, v4
	v_mov_b32_e32 v4, v2
	s_nop 1
	v_permlane16_swap_b32_e32 v4, v2
	s_waitcnt lgkmcnt(0)
	v_add_f32_e32 v2, v2, v4
	v_fmamk_f32 v2, v2, 0x3c000000, v244
	v_rsq_f32_e32 v86, v2
	s_nop 1
	v_mov_b32_dpp v2, v3 quad_perm:[1,0,3,2] row_mask:0xf bank_mask:0xf
	v_lshl_add_u64 v[4:5], v[148:149], 1, s[4:5]
	s_waitcnt lgkmcnt(0)
	v_add_f32_e32 v2, v3, v2
	s_nop 1
	v_mov_b32_dpp v3, v2 quad_perm:[2,3,0,1] row_mask:0xf bank_mask:0xf
	s_waitcnt lgkmcnt(0)
	v_add_f32_e32 v2, v2, v3
	s_nop 1
	v_mov_b32_dpp v3, v2 row_half_mirror row_mask:0xf bank_mask:0xf
	s_waitcnt lgkmcnt(0)
	v_add_f32_e32 v2, v2, v3
	s_nop 1
	v_mov_b32_dpp v3, v2 row_mirror row_mask:0xf bank_mask:0xf
	s_waitcnt lgkmcnt(0)
	v_add_f32_e32 v2, v2, v3
	v_mov_b32_e32 v3, v2
	s_nop 1
	v_permlane16_swap_b32_e32 v3, v2
	s_waitcnt lgkmcnt(0)
; __device__ __forceinline__ void attn_unit(LAS unsigned char* lds, const bf16_t* Z, bf16_t* A2, const float* tabg, int seq_base, int S, int h, int qb, float lam) {
;     ...
;         for (int r = 0; r < 16; ++r) { const int q = (r & 3) + 8 * (r >> 2) + 4 * hie;
;             bf16_t* orow = A2 + (size_t)(seq_base + qlo + q) * DM + h * 128 + r32e;
; #pragma unroll
;             for (int d = 0; d < 4; ++d) orow[d * 32] = (bf16_t)(pk2(O[d][r] * ss[r], 0.f) & 0xffffu); }
	v_add_f32_e32 v2, v2, v3
	v_fmamk_f32 v2, v2, 0x3c000000, v244
	v_rsq_f32_e32 v87, v2
	v_lshl_add_u32 v2, v159, 2, s14
	v_ashrrev_i32_e32 v3, 31, v2
	v_lshlrev_b64 v[70:71], 11, v[2:3]
	v_mul_f32_e32 v3, v10, v80
	v_lshl_add_u64 v[70:71], v[4:5], 0, v[70:71]
	v_cvt_pk_bf16_f32 v3, v3, s0
	global_store_short v[70:71], v3, off
	v_mul_f32_e32 v3, v11, v80
	v_cvt_pk_bf16_f32 v3, v3, s0
	global_store_short v[70:71], v3, off offset:64
	v_mul_f32_e32 v3, v12, v80
	v_cvt_pk_bf16_f32 v3, v3, s0
	global_store_short v[70:71], v3, off offset:128
	v_mul_f32_e32 v3, v13, v80
	v_or_b32_e32 v10, 1, v2
	v_cvt_pk_bf16_f32 v3, v3, s0
	v_ashrrev_i32_e32 v11, 31, v10
	global_store_short v[70:71], v3, off offset:192
	v_lshlrev_b64 v[10:11], 11, v[10:11]
	v_mul_f32_e32 v3, v9, v77
	v_lshl_add_u64 v[10:11], v[4:5], 0, v[10:11]
	v_cvt_pk_bf16_f32 v3, v3, s0
	global_store_short v[10:11], v3, off
	v_mul_f32_e32 v3, v7, v77
	v_cvt_pk_bf16_f32 v3, v3, s0
	global_store_short v[10:11], v3, off offset:64
	v_mul_f32_e32 v3, v8, v77
	v_cvt_pk_bf16_f32 v3, v3, s0
	global_store_short v[10:11], v3, off offset:128
	v_mul_f32_e32 v3, v6, v77
	v_or_b32_e32 v6, 2, v2
	v_cvt_pk_bf16_f32 v3, v3, s0
	v_ashrrev_i32_e32 v7, 31, v6
	global_store_short v[10:11], v3, off offset:192
	v_lshlrev_b64 v[6:7], 11, v[6:7]
	v_mul_f32_e32 v3, v19, v78
	v_lshl_add_u64 v[6:7], v[4:5], 0, v[6:7]
	v_cvt_pk_bf16_f32 v3, v3, s0
	global_store_short v[6:7], v3, off
	v_mul_f32_e32 v3, v18, v78
	v_cvt_pk_bf16_f32 v3, v3, s0
	global_store_short v[6:7], v3, off offset:64
	v_mul_f32_e32 v3, v20, v78
	v_cvt_pk_bf16_f32 v3, v3, s0
	global_store_short v[6:7], v3, off offset:128
	v_mul_f32_e32 v3, v21, v78
	v_cvt_pk_bf16_f32 v3, v3, s0
	global_store_short v[6:7], v3, off offset:192
	v_or_b32_e32 v6, 3, v2
	v_ashrrev_i32_e32 v7, 31, v6
	v_lshlrev_b64 v[6:7], 11, v[6:7]
	v_mul_f32_e32 v3, v17, v73
	v_lshl_add_u64 v[6:7], v[4:5], 0, v[6:7]
	v_cvt_pk_bf16_f32 v3, v3, s0
	global_store_short v[6:7], v3, off
	v_mul_f32_e32 v3, v15, v73
	v_cvt_pk_bf16_f32 v3, v3, s0
	global_store_short v[6:7], v3, off offset:64
	v_mul_f32_e32 v3, v16, v73
	v_cvt_pk_bf16_f32 v3, v3, s0
	global_store_short v[6:7], v3, off offset:128
	v_mul_f32_e32 v3, v14, v73
	v_cvt_pk_bf16_f32 v3, v3, s0
	global_store_short v[6:7], v3, off offset:192
	v_add_u32_e32 v6, 8, v2
	v_ashrrev_i32_e32 v7, 31, v6
	v_lshlrev_b64 v[6:7], 11, v[6:7]
	v_mul_f32_e32 v3, v27, v74
	v_lshl_add_u64 v[6:7], v[4:5], 0, v[6:7]
	v_cvt_pk_bf16_f32 v3, v3, s0
	global_store_short v[6:7], v3, off
	v_mul_f32_e32 v3, v26, v74
	v_cvt_pk_bf16_f32 v3, v3, s0
	global_store_short v[6:7], v3, off offset:64
	v_mul_f32_e32 v3, v28, v74
	v_cvt_pk_bf16_f32 v3, v3, s0
	global_store_short v[6:7], v3, off offset:128
	v_mul_f32_e32 v3, v29, v74
	v_cvt_pk_bf16_f32 v3, v3, s0
	global_store_short v[6:7], v3, off offset:192
	v_add_u32_e32 v6, 9, v2
	v_ashrrev_i32_e32 v7, 31, v6
	v_lshlrev_b64 v[6:7], 11, v[6:7]
	v_mul_f32_e32 v3, v25, v82
	v_lshl_add_u64 v[6:7], v[4:5], 0, v[6:7]
	v_cvt_pk_bf16_f32 v3, v3, s0
	global_store_short v[6:7], v3, off
	v_mul_f32_e32 v3, v23, v82
	v_cvt_pk_bf16_f32 v3, v3, s0
	global_store_short v[6:7], v3, off offset:64
	v_mul_f32_e32 v3, v24, v82
	v_cvt_pk_bf16_f32 v3, v3, s0
	global_store_short v[6:7], v3, off offset:128
	v_mul_f32_e32 v3, v22, v82
	v_cvt_pk_bf16_f32 v3, v3, s0
	global_store_short v[6:7], v3, off offset:192
	v_add_u32_e32 v6, 10, v2
	v_ashrrev_i32_e32 v7, 31, v6
	v_lshlrev_b64 v[6:7], 11, v[6:7]
	v_mul_f32_e32 v3, v30, v72
	v_lshl_add_u64 v[6:7], v[4:5], 0, v[6:7]
	v_cvt_pk_bf16_f32 v3, v3, s0
	global_store_short v[6:7], v3, off
	v_mul_f32_e32 v3, v31, v72
	v_cvt_pk_bf16_f32 v3, v3, s0
	global_store_short v[6:7], v3, off offset:64
	v_mul_f32_e32 v3, v32, v72
	v_cvt_pk_bf16_f32 v3, v3, s0
	global_store_short v[6:7], v3, off offset:128
	v_mul_f32_e32 v3, v45, v72
	v_cvt_pk_bf16_f32 v3, v3, s0
	global_store_short v[6:7], v3, off offset:192
	v_add_u32_e32 v6, 11, v2
	v_ashrrev_i32_e32 v7, 31, v6
	v_lshlrev_b64 v[6:7], 11, v[6:7]
	v_mul_f32_e32 v3, v41, v81
	v_lshl_add_u64 v[6:7], v[4:5], 0, v[6:7]
	v_cvt_pk_bf16_f32 v3, v3, s0
	global_store_short v[6:7], v3, off
	v_mul_f32_e32 v3, v38, v81
	v_cvt_pk_bf16_f32 v3, v3, s0
	global_store_short v[6:7], v3, off offset:64
	v_mul_f32_e32 v3, v40, v81
	v_cvt_pk_bf16_f32 v3, v3, s0
	global_store_short v[6:7], v3, off offset:128
	v_mul_f32_e32 v3, v39, v81
	v_cvt_pk_bf16_f32 v3, v3, s0
; __device__ __forceinline__ void attn_unit(LAS unsigned char* lds, const bf16_t* Z, bf16_t* A2, const float* tabg, int seq_base, int S, int h, int qb, float lam) {
;     ...
;         for (int r = 0; r < 16; ++r) { const int q = (r & 3) + 8 * (r >> 2) + 4 * hie;
;             bf16_t* orow = A2 + (size_t)(seq_base + qlo + q) * DM + h * 128 + r32e;
; #pragma unroll
;             for (int d = 0; d < 4; ++d) orow[d * 32] = (bf16_t)(pk2(O[d][r] * ss[r], 0.f) & 0xffffu); }
	global_store_short v[6:7], v3, off offset:192
	v_add_u32_e32 v6, 16, v2
	v_ashrrev_i32_e32 v7, 31, v6
	v_lshlrev_b64 v[6:7], 11, v[6:7]
	v_mul_f32_e32 v3, v37, v79
	v_lshl_add_u64 v[6:7], v[4:5], 0, v[6:7]
	v_cvt_pk_bf16_f32 v3, v3, s0
	global_store_short v[6:7], v3, off
	v_mul_f32_e32 v3, v42, v79
	v_cvt_pk_bf16_f32 v3, v3, s0
	global_store_short v[6:7], v3, off offset:64
	v_mul_f32_e32 v3, v43, v79
	v_cvt_pk_bf16_f32 v3, v3, s0
	global_store_short v[6:7], v3, off offset:128
	v_mul_f32_e32 v3, v44, v79
	v_cvt_pk_bf16_f32 v3, v3, s0
	global_store_short v[6:7], v3, off offset:192
	v_add_u32_e32 v6, 17, v2
	v_ashrrev_i32_e32 v7, 31, v6
	v_lshlrev_b64 v[6:7], 11, v[6:7]
	v_mul_f32_e32 v3, v36, v75
	v_lshl_add_u64 v[6:7], v[4:5], 0, v[6:7]
	v_cvt_pk_bf16_f32 v3, v3, s0
	global_store_short v[6:7], v3, off
	v_mul_f32_e32 v3, v34, v75
	v_cvt_pk_bf16_f32 v3, v3, s0
	global_store_short v[6:7], v3, off offset:64
	v_mul_f32_e32 v3, v35, v75
	v_cvt_pk_bf16_f32 v3, v3, s0
	global_store_short v[6:7], v3, off offset:128
	v_mul_f32_e32 v3, v33, v75
	v_cvt_pk_bf16_f32 v3, v3, s0
	global_store_short v[6:7], v3, off offset:192
	v_add_u32_e32 v6, 18, v2
	v_ashrrev_i32_e32 v7, 31, v6
	v_lshlrev_b64 v[6:7], 11, v[6:7]
	v_mul_f32_e32 v3, v51, v76
	v_lshl_add_u64 v[6:7], v[4:5], 0, v[6:7]
	v_cvt_pk_bf16_f32 v3, v3, s0
	global_store_short v[6:7], v3, off
	v_mul_f32_e32 v3, v50, v76
	v_cvt_pk_bf16_f32 v3, v3, s0
	global_store_short v[6:7], v3, off offset:64
	v_mul_f32_e32 v3, v52, v76
	v_cvt_pk_bf16_f32 v3, v3, s0
	global_store_short v[6:7], v3, off offset:128
	v_mul_f32_e32 v3, v53, v76
	v_cvt_pk_bf16_f32 v3, v3, s0
	global_store_short v[6:7], v3, off offset:192
	v_add_u32_e32 v6, 19, v2
	v_ashrrev_i32_e32 v7, 31, v6
	v_lshlrev_b64 v[6:7], 11, v[6:7]
	v_mul_f32_e32 v3, v49, v83
	v_lshl_add_u64 v[6:7], v[4:5], 0, v[6:7]
	v_cvt_pk_bf16_f32 v3, v3, s0
	global_store_short v[6:7], v3, off
	v_mul_f32_e32 v3, v47, v83
	v_cvt_pk_bf16_f32 v3, v3, s0
	global_store_short v[6:7], v3, off offset:64
	v_mul_f32_e32 v3, v48, v83
	v_cvt_pk_bf16_f32 v3, v3, s0
	global_store_short v[6:7], v3, off offset:128
	v_mul_f32_e32 v3, v46, v83
	v_cvt_pk_bf16_f32 v3, v3, s0
	global_store_short v[6:7], v3, off offset:192
	v_add_u32_e32 v6, 24, v2
	v_ashrrev_i32_e32 v7, 31, v6
	v_lshlrev_b64 v[6:7], 11, v[6:7]
	v_mul_f32_e32 v3, v59, v84
	v_lshl_add_u64 v[6:7], v[4:5], 0, v[6:7]
	v_cvt_pk_bf16_f32 v3, v3, s0
	global_store_short v[6:7], v3, off
	v_mul_f32_e32 v3, v58, v84
	v_cvt_pk_bf16_f32 v3, v3, s0
	global_store_short v[6:7], v3, off offset:64
	v_mul_f32_e32 v3, v60, v84
	v_cvt_pk_bf16_f32 v3, v3, s0
	global_store_short v[6:7], v3, off offset:128
	v_mul_f32_e32 v3, v61, v84
	v_cvt_pk_bf16_f32 v3, v3, s0
	global_store_short v[6:7], v3, off offset:192
	v_add_u32_e32 v6, 25, v2
	v_ashrrev_i32_e32 v7, 31, v6
	v_lshlrev_b64 v[6:7], 11, v[6:7]
	v_mul_f32_e32 v3, v57, v85
	v_lshl_add_u64 v[6:7], v[4:5], 0, v[6:7]
	v_cvt_pk_bf16_f32 v3, v3, s0
	global_store_short v[6:7], v3, off
	v_mul_f32_e32 v3, v55, v85
	v_cvt_pk_bf16_f32 v3, v3, s0
	global_store_short v[6:7], v3, off offset:64
	v_mul_f32_e32 v3, v56, v85
	v_cvt_pk_bf16_f32 v3, v3, s0
	global_store_short v[6:7], v3, off offset:128
	v_mul_f32_e32 v3, v54, v85
	v_cvt_pk_bf16_f32 v3, v3, s0
	global_store_short v[6:7], v3, off offset:192
	v_add_u32_e32 v6, 26, v2
	v_ashrrev_i32_e32 v7, 31, v6
	v_lshlrev_b64 v[6:7], 11, v[6:7]
	v_mul_f32_e32 v3, v62, v86
	v_lshl_add_u64 v[6:7], v[4:5], 0, v[6:7]
	v_cvt_pk_bf16_f32 v3, v3, s0
	global_store_short v[6:7], v3, off
	v_mul_f32_e32 v3, v63, v86
	v_cvt_pk_bf16_f32 v3, v3, s0
	global_store_short v[6:7], v3, off offset:64
	v_mul_f32_e32 v3, v64, v86
	v_cvt_pk_bf16_f32 v3, v3, s0
	global_store_short v[6:7], v3, off offset:128
	v_mul_f32_e32 v3, v69, v86
	v_cvt_pk_bf16_f32 v3, v3, s0
	v_add_u32_e32 v2, 27, v2
	global_store_short v[6:7], v3, off offset:192
	v_ashrrev_i32_e32 v3, 31, v2
	v_lshlrev_b64 v[2:3], 11, v[2:3]
	v_lshl_add_u64 v[2:3], v[4:5], 0, v[2:3]
	v_mul_f32_e32 v4, v68, v87
	v_cvt_pk_bf16_f32 v4, v4, s0
	global_store_short v[2:3], v4, off
	v_mul_f32_e32 v4, v66, v87
	v_cvt_pk_bf16_f32 v4, v4, s0
	global_store_short v[2:3], v4, off offset:64
	v_mul_f32_e32 v4, v67, v87
	v_cvt_pk_bf16_f32 v4, v4, s0
	global_store_short v[2:3], v4, off offset:128
	v_mul_f32_e32 v4, v65, v87
	v_cvt_pk_bf16_f32 v4, v4, s0
	global_store_short v[2:3], v4, off offset:192

; __device__ __forceinline__ void attn_unit(LAS unsigned char* lds, const bf16_t* Z, bf16_t* A2, const float* tabg, int seq_base, int S, int h, int qb, float lam) {
;     ...
;     __syncthreads();
;     if (m == 0) {
;         float ss[16];
; #pragma unroll
;         for (int r = 0; r < 16; ++r) { float q = 0.f;
; #pragma unroll
;             for (int d = 0; d < 4; ++d) { const float o = O[d][r] - X[(d * 16 + r) * 64]; O[d][r] = o; q += o * o; }
;             ss[r] = q; }
; #pragma unroll
;         for (int r = 0; r < 16; ++r) { float q = ss[r];
; #pragma unroll
;             for (int o = 1; o < 32; o <<= 1) q += __shfl_xor(q, o);
;             ss[r] = __builtin_amdgcn_rsqf(q * (1.0f / 128.0f) + RMS_EPS); }
.LBB0_346:
	s_andn2_b64 vcc, exec, s[4:5]
	s_waitcnt lgkmcnt(0)
	s_barrier
	s_cbranch_vccnz .LBB0_281
	ds_read2st64_b32 v[28:29], v69 offset0:16 offset1:17
	ds_read2st64_b32 v[30:31], v69 offset0:32 offset1:33
	ds_read2st64_b32 v[26:27], v69 offset1:1
	ds_read2st64_b32 v[32:33], v69 offset0:48 offset1:49
	ds_read2st64_b32 v[50:51], v69 offset0:54 offset1:55
	ds_read2st64_b32 v[48:49], v69 offset0:52 offset1:53
	s_waitcnt lgkmcnt(4)
	v_sub_f32_e32 v12, v12, v30
	v_sub_f32_e32 v8, v8, v31
	ds_read2st64_b32 v[30:31], v69 offset0:34 offset1:35
	s_waitcnt lgkmcnt(3)
	v_sub_f32_e32 v13, v9, v32
	v_sub_f32_e32 v6, v6, v33
	ds_read2st64_b32 v[32:33], v69 offset0:50 offset1:51
	ds_read2st64_b32 v[34:35], v69 offset0:36 offset1:37
	s_waitcnt lgkmcnt(2)
	v_sub_f32_e32 v20, v20, v30
	v_sub_f32_e32 v16, v16, v31
	ds_read2st64_b32 v[30:31], v69 offset0:4 offset1:5
	v_sub_f32_e32 v11, v11, v28
	v_sub_f32_e32 v9, v7, v27
	v_sub_f32_e32 v7, v21, v29
	ds_read2st64_b32 v[28:29], v69 offset0:18 offset1:19
	v_sub_f32_e32 v10, v10, v26
	ds_read2st64_b32 v[26:27], v69 offset0:2 offset1:3
	s_waitcnt lgkmcnt(4)
	v_sub_f32_e32 v21, v17, v32
	v_sub_f32_e32 v14, v14, v33
	s_waitcnt lgkmcnt(1)
	v_sub_f32_e32 v18, v18, v28
	ds_read2st64_b32 v[32:33], v69 offset0:20 offset1:21
	v_sub_f32_e32 v28, v89, v34
	v_sub_f32_e32 v24, v24, v35
	ds_read2st64_b32 v[34:35], v69 offset0:22 offset1:23
	v_sub_f32_e32 v25, v4, v31
	v_sub_f32_e32 v45, v38, v50
	v_sub_f32_e32 v39, v39, v51
	ds_read2st64_b32 v[50:51], v69 offset0:40 offset1:41
	v_sub_f32_e32 v22, v22, v49
	s_waitcnt lgkmcnt(1)
	v_sub_f32_e32 v31, v72, v34
	v_sub_f32_e32 v38, v42, v35
	ds_read2st64_b32 v[34:35], v69 offset0:8 offset1:9
	v_sub_f32_e32 v19, v19, v26
	v_sub_f32_e32 v17, v15, v27
	v_sub_f32_e32 v15, v92, v29
	v_sub_f32_e32 v26, v90, v32
	v_sub_f32_e32 v29, v88, v48
	v_sub_f32_e32 v23, v23, v33
	ds_read2st64_b32 v[32:33], v69 offset0:6 offset1:7
	ds_read2st64_b32 v[48:49], v69 offset0:38 offset1:39
	ds_read2st64_b32 v[82:83], v69 offset0:56 offset1:57
	v_sub_f32_e32 v27, v91, v30
	s_waitcnt lgkmcnt(3)
	v_sub_f32_e32 v36, v36, v35
	s_waitcnt lgkmcnt(2)
	v_sub_f32_e32 v30, v87, v32
	s_waitcnt lgkmcnt(1)
	v_sub_f32_e32 v32, v41, v48
	v_sub_f32_e32 v40, v40, v49
	ds_read2st64_b32 v[48:49], v69 offset0:24 offset1:25
	v_sub_f32_e32 v41, v37, v33
	v_sub_f32_e32 v37, v86, v34
	s_waitcnt lgkmcnt(1)
	v_sub_f32_e32 v44, v44, v82
	v_sub_f32_e32 v33, v76, v83
	ds_read2st64_b32 v[82:83], v69 offset0:26 offset1:27
	s_waitcnt lgkmcnt(1)
	v_sub_f32_e32 v42, v85, v48
	v_sub_f32_e32 v34, v75, v49
	v_sub_f32_e32 v35, v84, v51
	ds_read2st64_b32 v[48:49], v69 offset0:10 offset1:11
	ds_read2st64_b32 v[86:87], v69 offset0:44 offset1:45
	ds_read2st64_b32 v[84:85], v69 offset0:58 offset1:59
	v_sub_f32_e32 v43, v43, v50
	s_waitcnt lgkmcnt(3)
	v_sub_f32_e32 v50, v70, v82
	v_sub_f32_e32 v47, v47, v83
	ds_read2st64_b32 v[82:83], v69 offset0:12 offset1:13
	s_waitcnt lgkmcnt(1)
	v_sub_f32_e32 v53, v53, v84
	v_sub_f32_e32 v46, v46, v85
	ds_read2st64_b32 v[84:85], v69 offset0:28 offset1:29
	v_sub_f32_e32 v51, v71, v48
	ds_read2st64_b32 v[70:71], v69 offset0:42 offset1:43
	ds_read2st64_b32 v[88:89], v69 offset0:60 offset1:61
	s_waitcnt lgkmcnt(3)
	v_sub_f32_e32 v59, v59, v82
	v_mul_f32_e32 v80, v11, v11
	v_fmac_f32_e32 v80, v10, v10
	s_waitcnt lgkmcnt(1)
	v_sub_f32_e32 v48, v61, v71
	s_waitcnt lgkmcnt(0)
	v_sub_f32_e32 v61, v57, v88
	v_sub_f32_e32 v57, v2, v83
	ds_read2st64_b32 v[82:83], v69 offset0:14 offset1:15
	v_fmac_f32_e32 v80, v12, v12
	v_fmac_f32_e32 v80, v13, v13
	v_sub_f32_e32 v58, v58, v84
	v_sub_f32_e32 v60, v60, v86
	v_sub_f32_e32 v55, v55, v85
	v_sub_f32_e32 v56, v56, v87
	v_sub_f32_e32 v54, v54, v89
	ds_read2st64_b32 v[84:85], v69 offset0:30 offset1:31
	ds_read2st64_b32 v[86:87], v69 offset0:46 offset1:47
	ds_read2st64_b32 v[88:89], v69 offset0:62 offset1:63
	s_waitcnt lgkmcnt(3)
	v_sub_f32_e32 v62, v62, v82
	s_nop 1
	v_mov_b32_dpp v82, v80 quad_perm:[1,0,3,2] row_mask:0xf bank_mask:0xf
	v_mul_f32_e32 v77, v7, v7
	v_fmac_f32_e32 v77, v9, v9
	v_fmac_f32_e32 v77, v8, v8
	v_fmac_f32_e32 v77, v6, v6
	s_waitcnt lgkmcnt(0)
	v_add_f32_e32 v80, v80, v82
	s_nop 1
	v_mov_b32_dpp v82, v80 quad_perm:[2,3,0,1] row_mask:0xf bank_mask:0xf
	v_mul_f32_e32 v78, v18, v18
	v_fmac_f32_e32 v78, v19, v19
	v_fmac_f32_e32 v78, v20, v20
	v_fmac_f32_e32 v78, v21, v21
	s_waitcnt lgkmcnt(0)
	v_add_f32_e32 v80, v80, v82
	s_nop 1
	v_mov_b32_dpp v82, v80 row_half_mirror row_mask:0xf bank_mask:0xf
	v_mul_f32_e32 v73, v15, v15
	v_fmac_f32_e32 v73, v17, v17
	v_fmac_f32_e32 v73, v16, v16
	v_fmac_f32_e32 v73, v14, v14
	s_waitcnt lgkmcnt(0)
	v_add_f32_e32 v80, v80, v82
	s_nop 1
	v_mov_b32_dpp v82, v80 row_mirror row_mask:0xf bank_mask:0xf
	v_mul_f32_e32 v74, v26, v26
	v_fmac_f32_e32 v74, v27, v27
	v_fmac_f32_e32 v74, v28, v28
	v_fmac_f32_e32 v74, v29, v29
	s_waitcnt lgkmcnt(0)
	v_add_f32_e32 v80, v80, v82
	v_mov_b32_e32 v82, v80
	s_nop 1
	v_permlane16_swap_b32_e32 v82, v80
	v_mul_f32_e32 v4, v23, v23
	v_fmac_f32_e32 v4, v25, v25
	v_fmac_f32_e32 v4, v24, v24
	v_fmac_f32_e32 v4, v22, v22
	s_waitcnt lgkmcnt(0)
	v_add_f32_e32 v80, v80, v82
	s_nop 1
	v_mov_b32_dpp v82, v77 quad_perm:[1,0,3,2] row_mask:0xf bank_mask:0xf
	v_mul_f32_e32 v72, v31, v31
	v_fmac_f32_e32 v72, v30, v30
	v_fmac_f32_e32 v72, v32, v32
	v_fmac_f32_e32 v72, v45, v45
	s_waitcnt lgkmcnt(0)
	v_add_f32_e32 v77, v77, v82
	s_nop 1
	v_mov_b32_dpp v82, v77 quad_perm:[2,3,0,1] row_mask:0xf bank_mask:0xf
	v_mul_f32_e32 v81, v38, v38
	v_fmac_f32_e32 v81, v41, v41
	v_fmac_f32_e32 v81, v40, v40
	v_fmac_f32_e32 v81, v39, v39
	s_waitcnt lgkmcnt(0)
; __device__ __forceinline__ void attn_unit(LAS unsigned char* lds, const bf16_t* Z, bf16_t* A2, const float* tabg, int seq_base, int S, int h, int qb, float lam) {
;     ...
;         for (int r = 0; r < 16; ++r) { float q = 0.f;
; #pragma unroll
;             for (int d = 0; d < 4; ++d) { const float o = O[d][r] - X[(d * 16 + r) * 64]; O[d][r] = o; q += o * o; }
;             ss[r] = q; }
; #pragma unroll
;         for (int r = 0; r < 16; ++r) { float q = ss[r];
; #pragma unroll
;             for (int o = 1; o < 32; o <<= 1) q += __shfl_xor(q, o);
;             ss[r] = __builtin_amdgcn_rsqf(q * (1.0f / 128.0f) + RMS_EPS); }
	v_add_f32_e32 v77, v77, v82
	s_nop 1
	v_mov_b32_dpp v82, v77 row_half_mirror row_mask:0xf bank_mask:0xf
	v_mul_f32_e32 v79, v42, v42
	v_fmac_f32_e32 v79, v37, v37
	v_fmac_f32_e32 v79, v43, v43
	v_fmac_f32_e32 v79, v44, v44
	s_waitcnt lgkmcnt(0)
	v_add_f32_e32 v77, v77, v82
	s_nop 1
	v_mov_b32_dpp v82, v77 row_mirror row_mask:0xf bank_mask:0xf
	v_mul_f32_e32 v75, v34, v34
	v_fmac_f32_e32 v75, v36, v36
	v_fmac_f32_e32 v75, v35, v35
	v_fmac_f32_e32 v75, v33, v33
	s_waitcnt lgkmcnt(0)
	v_add_f32_e32 v77, v77, v82
	v_mov_b32_e32 v82, v77
	s_nop 1
	v_permlane16_swap_b32_e32 v82, v77
	v_mul_f32_e32 v76, v50, v50
	v_fmac_f32_e32 v76, v51, v51
	v_sub_f32_e32 v52, v52, v70
	v_fmac_f32_e32 v76, v52, v52
	s_waitcnt lgkmcnt(0)
	v_add_f32_e32 v77, v77, v82
	s_nop 1
	v_mov_b32_dpp v82, v78 quad_perm:[1,0,3,2] row_mask:0xf bank_mask:0xf
	v_fmac_f32_e32 v76, v53, v53
	v_sub_f32_e32 v49, v5, v49
	v_mul_f32_e32 v5, v47, v47
	v_fmac_f32_e32 v5, v49, v49
	s_waitcnt lgkmcnt(0)
	v_add_f32_e32 v78, v78, v82
	s_nop 1
	v_mov_b32_dpp v82, v78 quad_perm:[2,3,0,1] row_mask:0xf bank_mask:0xf
	v_fmac_f32_e32 v5, v48, v48
	v_fmac_f32_e32 v5, v46, v46
	v_mul_f32_e32 v71, v58, v58
	v_fmac_f32_e32 v71, v59, v59
	s_waitcnt lgkmcnt(0)
	v_add_f32_e32 v78, v78, v82
	s_nop 1
	v_mov_b32_dpp v82, v78 row_half_mirror row_mask:0xf bank_mask:0xf
	v_fmac_f32_e32 v71, v60, v60
	v_fmac_f32_e32 v71, v61, v61
	v_sub_f32_e32 v69, v68, v88
	v_sub_f32_e32 v68, v3, v83
	s_waitcnt lgkmcnt(0)
	v_add_f32_e32 v78, v78, v82
	s_nop 1
	v_mov_b32_dpp v82, v78 row_mirror row_mask:0xf bank_mask:0xf
	v_mul_f32_e32 v2, v55, v55
	v_fmac_f32_e32 v2, v57, v57
	v_fmac_f32_e32 v2, v56, v56
	v_fmac_f32_e32 v2, v54, v54
	s_waitcnt lgkmcnt(0)
	v_add_f32_e32 v78, v78, v82
	v_mov_b32_e32 v82, v78
	s_nop 1
	v_permlane16_swap_b32_e32 v82, v78
	v_sub_f32_e32 v63, v63, v84
	v_mul_f32_e32 v70, v63, v63
	v_fmac_f32_e32 v70, v62, v62
	v_sub_f32_e32 v64, v64, v86
	s_waitcnt lgkmcnt(0)
	v_add_f32_e32 v78, v78, v82
	s_nop 1
	v_mov_b32_dpp v82, v73 quad_perm:[1,0,3,2] row_mask:0xf bank_mask:0xf
	v_fmac_f32_e32 v70, v64, v64
	v_fmac_f32_e32 v70, v69, v69
	v_sub_f32_e32 v66, v66, v85
	v_mul_f32_e32 v3, v66, v66
	s_waitcnt lgkmcnt(0)
	v_add_f32_e32 v73, v73, v82
	s_nop 1
	v_mov_b32_dpp v82, v73 quad_perm:[2,3,0,1] row_mask:0xf bank_mask:0xf
	v_fmac_f32_e32 v3, v68, v68
	v_sub_f32_e32 v67, v67, v87
	v_fmac_f32_e32 v3, v67, v67
	v_sub_f32_e32 v65, v65, v89
	s_waitcnt lgkmcnt(0)
	v_add_f32_e32 v73, v73, v82
	s_nop 1
	v_mov_b32_dpp v82, v73 row_half_mirror row_mask:0xf bank_mask:0xf
	v_fmac_f32_e32 v3, v65, v65
	v_fmamk_f32 v80, v80, 0x3c000000, v244
	v_rsq_f32_e32 v80, v80
	s_lshl_b32 s4, s15, 1
	s_waitcnt lgkmcnt(0)
	v_add_f32_e32 v73, v73, v82
	s_nop 1
	v_mov_b32_dpp v82, v73 row_mirror row_mask:0xf bank_mask:0xf
	s_add_u32 s4, s6, s4
	v_ashrrev_i32_e32 v149, 31, v148
	s_addc_u32 s5, s7, 0
	v_fmamk_f32 v77, v77, 0x3c000000, v244
	s_waitcnt lgkmcnt(0)
	v_add_f32_e32 v73, v73, v82
	v_mov_b32_e32 v82, v73
	s_nop 1
	v_permlane16_swap_b32_e32 v82, v73
	v_rsq_f32_e32 v77, v77
	v_fmamk_f32 v78, v78, 0x3c000000, v244
	v_rsq_f32_e32 v78, v78
	s_waitcnt lgkmcnt(0)
	v_add_f32_e32 v73, v73, v82
	s_nop 1
	v_mov_b32_dpp v82, v74 quad_perm:[1,0,3,2] row_mask:0xf bank_mask:0xf
	v_fmamk_f32 v73, v73, 0x3c000000, v244
	v_rsq_f32_e32 v73, v73
	s_waitcnt lgkmcnt(0)
	v_add_f32_e32 v74, v74, v82
	s_nop 1
	v_mov_b32_dpp v82, v74 quad_perm:[2,3,0,1] row_mask:0xf bank_mask:0xf
	s_waitcnt lgkmcnt(0)
	v_add_f32_e32 v74, v74, v82
	s_nop 1
	v_mov_b32_dpp v82, v74 row_half_mirror row_mask:0xf bank_mask:0xf
	s_waitcnt lgkmcnt(0)
	v_add_f32_e32 v74, v74, v82
	s_nop 1
	v_mov_b32_dpp v82, v74 row_mirror row_mask:0xf bank_mask:0xf
	s_waitcnt lgkmcnt(0)
	v_add_f32_e32 v74, v74, v82
	v_mov_b32_e32 v82, v74
	s_nop 1
	v_permlane16_swap_b32_e32 v82, v74
	s_waitcnt lgkmcnt(0)
	v_add_f32_e32 v74, v74, v82
	s_nop 1
	v_mov_b32_dpp v82, v4 quad_perm:[1,0,3,2] row_mask:0xf bank_mask:0xf
	v_fmamk_f32 v74, v74, 0x3c000000, v244
	v_rsq_f32_e32 v74, v74
	s_waitcnt lgkmcnt(0)
	v_add_f32_e32 v4, v4, v82
	s_nop 1
	v_mov_b32_dpp v82, v4 quad_perm:[2,3,0,1] row_mask:0xf bank_mask:0xf
	s_waitcnt lgkmcnt(0)
	v_add_f32_e32 v4, v4, v82
	s_nop 1
	v_mov_b32_dpp v82, v4 row_half_mirror row_mask:0xf bank_mask:0xf
	s_waitcnt lgkmcnt(0)
	v_add_f32_e32 v4, v4, v82
	s_nop 1
	v_mov_b32_dpp v82, v4 row_mirror row_mask:0xf bank_mask:0xf
	s_waitcnt lgkmcnt(0)
	v_add_f32_e32 v4, v4, v82
	v_mov_b32_e32 v82, v4
	s_nop 1
	v_permlane16_swap_b32_e32 v82, v4
	s_waitcnt lgkmcnt(0)
	v_add_f32_e32 v4, v4, v82
	v_fmamk_f32 v4, v4, 0x3c000000, v244
	v_rsq_f32_e32 v82, v4
	s_nop 1
	v_mov_b32_dpp v4, v72 quad_perm:[1,0,3,2] row_mask:0xf bank_mask:0xf
	s_waitcnt lgkmcnt(0)
	v_add_f32_e32 v4, v72, v4
	s_nop 1
	v_mov_b32_dpp v72, v4 quad_perm:[2,3,0,1] row_mask:0xf bank_mask:0xf
	s_waitcnt lgkmcnt(0)
	v_add_f32_e32 v4, v4, v72
	s_nop 1
	v_mov_b32_dpp v72, v4 row_half_mirror row_mask:0xf bank_mask:0xf
	s_waitcnt lgkmcnt(0)
	v_add_f32_e32 v4, v4, v72
	s_nop 1
	v_mov_b32_dpp v72, v4 row_mirror row_mask:0xf bank_mask:0xf
	s_waitcnt lgkmcnt(0)
	v_add_f32_e32 v4, v4, v72
	v_mov_b32_e32 v72, v4
	s_nop 1
	v_permlane16_swap_b32_e32 v72, v4
	s_waitcnt lgkmcnt(0)
	v_add_f32_e32 v4, v4, v72
	v_fmamk_f32 v4, v4, 0x3c000000, v244
	v_rsq_f32_e32 v72, v4
	s_nop 1
	v_mov_b32_dpp v4, v81 quad_perm:[1,0,3,2] row_mask:0xf bank_mask:0xf
	s_waitcnt lgkmcnt(0)
	v_add_f32_e32 v4, v81, v4
	s_nop 1
	v_mov_b32_dpp v81, v4 quad_perm:[2,3,0,1] row_mask:0xf bank_mask:0xf
	s_waitcnt lgkmcnt(0)
	v_add_f32_e32 v4, v4, v81
	s_nop 1
	v_mov_b32_dpp v81, v4 row_half_mirror row_mask:0xf bank_mask:0xf
	s_waitcnt lgkmcnt(0)
; __device__ __forceinline__ void attn_unit(LAS unsigned char* lds, const bf16_t* Z, bf16_t* A2, const float* tabg, int seq_base, int S, int h, int qb, float lam) {
;     ...
;         for (int r = 0; r < 16; ++r) { float q = ss[r];
; #pragma unroll
;             for (int o = 1; o < 32; o <<= 1) q += __shfl_xor(q, o);
;             ss[r] = __builtin_amdgcn_rsqf(q * (1.0f / 128.0f) + RMS_EPS); }
	v_add_f32_e32 v4, v4, v81
	s_nop 1
	v_mov_b32_dpp v81, v4 row_mirror row_mask:0xf bank_mask:0xf
	s_waitcnt lgkmcnt(0)
	v_add_f32_e32 v4, v4, v81
	v_mov_b32_e32 v81, v4
	s_nop 1
	v_permlane16_swap_b32_e32 v81, v4
	s_waitcnt lgkmcnt(0)
	v_add_f32_e32 v4, v4, v81
	v_fmamk_f32 v4, v4, 0x3c000000, v244
	v_rsq_f32_e32 v81, v4
	s_nop 1
	v_mov_b32_dpp v4, v79 quad_perm:[1,0,3,2] row_mask:0xf bank_mask:0xf
	s_waitcnt lgkmcnt(0)
	v_add_f32_e32 v4, v79, v4
	s_nop 1
	v_mov_b32_dpp v79, v4 quad_perm:[2,3,0,1] row_mask:0xf bank_mask:0xf
	s_waitcnt lgkmcnt(0)
	v_add_f32_e32 v4, v4, v79
	s_nop 1
	v_mov_b32_dpp v79, v4 row_half_mirror row_mask:0xf bank_mask:0xf
	s_waitcnt lgkmcnt(0)
	v_add_f32_e32 v4, v4, v79
	s_nop 1
	v_mov_b32_dpp v79, v4 row_mirror row_mask:0xf bank_mask:0xf
	s_waitcnt lgkmcnt(0)
	v_add_f32_e32 v4, v4, v79
	v_mov_b32_e32 v79, v4
	s_nop 1
	v_permlane16_swap_b32_e32 v79, v4
	s_waitcnt lgkmcnt(0)
	v_add_f32_e32 v4, v4, v79
	v_fmamk_f32 v4, v4, 0x3c000000, v244
	v_rsq_f32_e32 v79, v4
	s_nop 1
	v_mov_b32_dpp v4, v75 quad_perm:[1,0,3,2] row_mask:0xf bank_mask:0xf
	s_waitcnt lgkmcnt(0)
	v_add_f32_e32 v4, v75, v4
	s_nop 1
	v_mov_b32_dpp v75, v4 quad_perm:[2,3,0,1] row_mask:0xf bank_mask:0xf
	s_waitcnt lgkmcnt(0)
	v_add_f32_e32 v4, v4, v75
	s_nop 1
	v_mov_b32_dpp v75, v4 row_half_mirror row_mask:0xf bank_mask:0xf
	s_waitcnt lgkmcnt(0)
	v_add_f32_e32 v4, v4, v75
	s_nop 1
	v_mov_b32_dpp v75, v4 row_mirror row_mask:0xf bank_mask:0xf
	s_waitcnt lgkmcnt(0)
	v_add_f32_e32 v4, v4, v75
	v_mov_b32_e32 v75, v4
	s_nop 1
	v_permlane16_swap_b32_e32 v75, v4
	s_waitcnt lgkmcnt(0)
	v_add_f32_e32 v4, v4, v75
	v_fmamk_f32 v4, v4, 0x3c000000, v244
	v_rsq_f32_e32 v75, v4
	s_nop 1
	v_mov_b32_dpp v4, v76 quad_perm:[1,0,3,2] row_mask:0xf bank_mask:0xf
	s_waitcnt lgkmcnt(0)
	v_add_f32_e32 v4, v76, v4
	s_nop 1
	v_mov_b32_dpp v76, v4 quad_perm:[2,3,0,1] row_mask:0xf bank_mask:0xf
	s_waitcnt lgkmcnt(0)
	v_add_f32_e32 v4, v4, v76
	s_nop 1
	v_mov_b32_dpp v76, v4 row_half_mirror row_mask:0xf bank_mask:0xf
	s_waitcnt lgkmcnt(0)
	v_add_f32_e32 v4, v4, v76
	s_nop 1
	v_mov_b32_dpp v76, v4 row_mirror row_mask:0xf bank_mask:0xf
	s_waitcnt lgkmcnt(0)
	v_add_f32_e32 v4, v4, v76
	v_mov_b32_e32 v76, v4
	s_nop 1
	v_permlane16_swap_b32_e32 v76, v4
	s_waitcnt lgkmcnt(0)
	v_add_f32_e32 v4, v4, v76
	v_fmamk_f32 v4, v4, 0x3c000000, v244
	v_rsq_f32_e32 v76, v4
	s_nop 1
	v_mov_b32_dpp v4, v5 quad_perm:[1,0,3,2] row_mask:0xf bank_mask:0xf
	s_waitcnt lgkmcnt(0)
	v_add_f32_e32 v4, v5, v4
	s_nop 1
	v_mov_b32_dpp v5, v4 quad_perm:[2,3,0,1] row_mask:0xf bank_mask:0xf
	s_waitcnt lgkmcnt(0)
	v_add_f32_e32 v4, v4, v5
	s_nop 1
	v_mov_b32_dpp v5, v4 row_half_mirror row_mask:0xf bank_mask:0xf
	s_waitcnt lgkmcnt(0)
	v_add_f32_e32 v4, v4, v5
	s_nop 1
	v_mov_b32_dpp v5, v4 row_mirror row_mask:0xf bank_mask:0xf
	s_waitcnt lgkmcnt(0)
	v_add_f32_e32 v4, v4, v5
	v_mov_b32_e32 v5, v4
	s_nop 1
	v_permlane16_swap_b32_e32 v5, v4
	s_waitcnt lgkmcnt(0)
	v_add_f32_e32 v4, v4, v5
	v_fmamk_f32 v4, v4, 0x3c000000, v244
	v_rsq_f32_e32 v83, v4
	s_nop 1
	v_mov_b32_dpp v4, v71 quad_perm:[1,0,3,2] row_mask:0xf bank_mask:0xf
	s_waitcnt lgkmcnt(0)
	v_add_f32_e32 v4, v71, v4
	s_nop 1
	v_mov_b32_dpp v5, v4 quad_perm:[2,3,0,1] row_mask:0xf bank_mask:0xf
	s_waitcnt lgkmcnt(0)
	v_add_f32_e32 v4, v4, v5
	s_nop 1
	v_mov_b32_dpp v5, v4 row_half_mirror row_mask:0xf bank_mask:0xf
	s_waitcnt lgkmcnt(0)
	v_add_f32_e32 v4, v4, v5
	s_nop 1
	v_mov_b32_dpp v5, v4 row_mirror row_mask:0xf bank_mask:0xf
	s_waitcnt lgkmcnt(0)
	v_add_f32_e32 v4, v4, v5
	v_mov_b32_e32 v5, v4
	s_nop 1
	v_permlane16_swap_b32_e32 v5, v4
	s_waitcnt lgkmcnt(0)
	v_add_f32_e32 v4, v4, v5
	v_fmamk_f32 v4, v4, 0x3c000000, v244
	v_rsq_f32_e32 v84, v4
	s_nop 1
	v_mov_b32_dpp v4, v2 quad_perm:[1,0,3,2] row_mask:0xf bank_mask:0xf
	s_waitcnt lgkmcnt(0)
	v_add_f32_e32 v2, v2, v4
	s_nop 1
	v_mov_b32_dpp v4, v2 quad_perm:[2,3,0,1] row_mask:0xf bank_mask:0xf
	s_waitcnt lgkmcnt(0)
	v_add_f32_e32 v2, v2, v4
	s_nop 1
	v_mov_b32_dpp v4, v2 row_half_mirror row_mask:0xf bank_mask:0xf
	s_waitcnt lgkmcnt(0)
	v_add_f32_e32 v2, v2, v4
	s_nop 1
	v_mov_b32_dpp v4, v2 row_mirror row_mask:0xf bank_mask:0xf
	s_waitcnt lgkmcnt(0)
	v_add_f32_e32 v2, v2, v4
	v_mov_b32_e32 v4, v2
	s_nop 1
	v_permlane16_swap_b32_e32 v4, v2
	s_waitcnt lgkmcnt(0)
	v_add_f32_e32 v2, v2, v4
	v_fmamk_f32 v2, v2, 0x3c000000, v244
	v_rsq_f32_e32 v85, v2
	s_nop 1
	v_mov_b32_dpp v2, v70 quad_perm:[1,0,3,2] row_mask:0xf bank_mask:0xf
	s_waitcnt lgkmcnt(0)
	v_add_f32_e32 v2, v70, v2
	s_nop 1
	v_mov_b32_dpp v4, v2 quad_perm:[2,3,0,1] row_mask:0xf bank_mask:0xf
	s_waitcnt lgkmcnt(0)
	v_add_f32_e32 v2, v2, v4
	s_nop 1
	v_mov_b32_dpp v4, v2 row_half_mirror row_mask:0xf bank_mask:0xf
	s_waitcnt lgkmcnt(0)
	v_add_f32_e32 v2, v2, v4
	s_nop 1
	v_mov_b32_dpp v4, v2 row_mirror row_mask:0xf bank_mask:0xf
	s_waitcnt lgkmcnt(0)
	v_add_f32_e32 v2, v2, v4
	v_mov_b32_e32 v4, v2
	s_nop 1
	v_permlane16_swap_b32_e32 v4, v2
	s_waitcnt lgkmcnt(0)
	v_add_f32_e32 v2, v2, v4
	v_fmamk_f32 v2, v2, 0x3c000000, v244
	v_rsq_f32_e32 v86, v2
	s_nop 1
	v_mov_b32_dpp v2, v3 quad_perm:[1,0,3,2] row_mask:0xf bank_mask:0xf
	v_lshl_add_u64 v[4:5], v[148:149], 1, s[4:5]
	s_waitcnt lgkmcnt(0)
	v_add_f32_e32 v2, v3, v2
	s_nop 1
	v_mov_b32_dpp v3, v2 quad_perm:[2,3,0,1] row_mask:0xf bank_mask:0xf
	s_waitcnt lgkmcnt(0)
	v_add_f32_e32 v2, v2, v3
	s_nop 1
	v_mov_b32_dpp v3, v2 row_half_mirror row_mask:0xf bank_mask:0xf
	s_waitcnt lgkmcnt(0)
	v_add_f32_e32 v2, v2, v3
	s_nop 1
	v_mov_b32_dpp v3, v2 row_mirror row_mask:0xf bank_mask:0xf
	s_waitcnt lgkmcnt(0)
	v_add_f32_e32 v2, v2, v3
	v_mov_b32_e32 v3, v2
	s_nop 1
	v_permlane16_swap_b32_e32 v3, v2
	s_waitcnt lgkmcnt(0)
; __device__ __forceinline__ void attn_unit(LAS unsigned char* lds, const bf16_t* Z, bf16_t* A2, const float* tabg, int seq_base, int S, int h, int qb, float lam) {
;     ...
;             ss[r] = __builtin_amdgcn_rsqf(q * (1.0f / 128.0f) + RMS_EPS); }
; #pragma unroll
;         for (int r = 0; r < 16; ++r) { const int q = (r & 3) + 8 * (r >> 2) + 4 * hie;
;             bf16_t* orow = A2 + (size_t)(seq_base + qlo + q) * DM + h * 128 + r32e;
; #pragma unroll
;             for (int d = 0; d < 4; ++d) orow[d * 32] = (bf16_t)(pk2(O[d][r] * ss[r], 0.f) & 0xffffu); }
	v_add_f32_e32 v2, v2, v3
	v_fmamk_f32 v2, v2, 0x3c000000, v244
	v_rsq_f32_e32 v87, v2
	v_lshl_add_u32 v2, v159, 2, s14
	v_ashrrev_i32_e32 v3, 31, v2
	v_lshlrev_b64 v[70:71], 11, v[2:3]
	v_mul_f32_e32 v3, v10, v80
	v_lshl_add_u64 v[70:71], v[4:5], 0, v[70:71]
	v_cvt_pk_bf16_f32 v3, v3, s0
	global_store_short v[70:71], v3, off
	v_mul_f32_e32 v3, v11, v80
	v_cvt_pk_bf16_f32 v3, v3, s0
	global_store_short v[70:71], v3, off offset:64
	v_mul_f32_e32 v3, v12, v80
	v_cvt_pk_bf16_f32 v3, v3, s0
	global_store_short v[70:71], v3, off offset:128
	v_mul_f32_e32 v3, v13, v80
	v_or_b32_e32 v10, 1, v2
	v_cvt_pk_bf16_f32 v3, v3, s0
	v_ashrrev_i32_e32 v11, 31, v10
	global_store_short v[70:71], v3, off offset:192
	v_lshlrev_b64 v[10:11], 11, v[10:11]
	v_mul_f32_e32 v3, v9, v77
	v_lshl_add_u64 v[10:11], v[4:5], 0, v[10:11]
	v_cvt_pk_bf16_f32 v3, v3, s0
	global_store_short v[10:11], v3, off
	v_mul_f32_e32 v3, v7, v77
	v_cvt_pk_bf16_f32 v3, v3, s0
	global_store_short v[10:11], v3, off offset:64
	v_mul_f32_e32 v3, v8, v77
	v_cvt_pk_bf16_f32 v3, v3, s0
	global_store_short v[10:11], v3, off offset:128
	v_mul_f32_e32 v3, v6, v77
	v_or_b32_e32 v6, 2, v2
	v_cvt_pk_bf16_f32 v3, v3, s0
	v_ashrrev_i32_e32 v7, 31, v6
	global_store_short v[10:11], v3, off offset:192
	v_lshlrev_b64 v[6:7], 11, v[6:7]
	v_mul_f32_e32 v3, v19, v78
	v_lshl_add_u64 v[6:7], v[4:5], 0, v[6:7]
	v_cvt_pk_bf16_f32 v3, v3, s0
	global_store_short v[6:7], v3, off
	v_mul_f32_e32 v3, v18, v78
	v_cvt_pk_bf16_f32 v3, v3, s0
	global_store_short v[6:7], v3, off offset:64
	v_mul_f32_e32 v3, v20, v78
	v_cvt_pk_bf16_f32 v3, v3, s0
	global_store_short v[6:7], v3, off offset:128
	v_mul_f32_e32 v3, v21, v78
	v_cvt_pk_bf16_f32 v3, v3, s0
	global_store_short v[6:7], v3, off offset:192
	v_or_b32_e32 v6, 3, v2
	v_ashrrev_i32_e32 v7, 31, v6
	v_lshlrev_b64 v[6:7], 11, v[6:7]
	v_mul_f32_e32 v3, v17, v73
	v_lshl_add_u64 v[6:7], v[4:5], 0, v[6:7]
	v_cvt_pk_bf16_f32 v3, v3, s0
	global_store_short v[6:7], v3, off
	v_mul_f32_e32 v3, v15, v73
	v_cvt_pk_bf16_f32 v3, v3, s0
	global_store_short v[6:7], v3, off offset:64
	v_mul_f32_e32 v3, v16, v73
	v_cvt_pk_bf16_f32 v3, v3, s0
	global_store_short v[6:7], v3, off offset:128
	v_mul_f32_e32 v3, v14, v73
	v_cvt_pk_bf16_f32 v3, v3, s0
	global_store_short v[6:7], v3, off offset:192
	v_add_u32_e32 v6, 8, v2
	v_ashrrev_i32_e32 v7, 31, v6
	v_lshlrev_b64 v[6:7], 11, v[6:7]
	v_mul_f32_e32 v3, v27, v74
	v_lshl_add_u64 v[6:7], v[4:5], 0, v[6:7]
	v_cvt_pk_bf16_f32 v3, v3, s0
	global_store_short v[6:7], v3, off
	v_mul_f32_e32 v3, v26, v74
	v_cvt_pk_bf16_f32 v3, v3, s0
	global_store_short v[6:7], v3, off offset:64
	v_mul_f32_e32 v3, v28, v74
	v_cvt_pk_bf16_f32 v3, v3, s0
	global_store_short v[6:7], v3, off offset:128
	v_mul_f32_e32 v3, v29, v74
	v_cvt_pk_bf16_f32 v3, v3, s0
	global_store_short v[6:7], v3, off offset:192
	v_add_u32_e32 v6, 9, v2
	v_ashrrev_i32_e32 v7, 31, v6
	v_lshlrev_b64 v[6:7], 11, v[6:7]
	v_mul_f32_e32 v3, v25, v82
	v_lshl_add_u64 v[6:7], v[4:5], 0, v[6:7]
	v_cvt_pk_bf16_f32 v3, v3, s0
	global_store_short v[6:7], v3, off
	v_mul_f32_e32 v3, v23, v82
	v_cvt_pk_bf16_f32 v3, v3, s0
	global_store_short v[6:7], v3, off offset:64
	v_mul_f32_e32 v3, v24, v82
	v_cvt_pk_bf16_f32 v3, v3, s0
	global_store_short v[6:7], v3, off offset:128
	v_mul_f32_e32 v3, v22, v82
	v_cvt_pk_bf16_f32 v3, v3, s0
	global_store_short v[6:7], v3, off offset:192
	v_add_u32_e32 v6, 10, v2
	v_ashrrev_i32_e32 v7, 31, v6
	v_lshlrev_b64 v[6:7], 11, v[6:7]
	v_mul_f32_e32 v3, v30, v72
	v_lshl_add_u64 v[6:7], v[4:5], 0, v[6:7]
	v_cvt_pk_bf16_f32 v3, v3, s0
	global_store_short v[6:7], v3, off
	v_mul_f32_e32 v3, v31, v72
	v_cvt_pk_bf16_f32 v3, v3, s0
	global_store_short v[6:7], v3, off offset:64
	v_mul_f32_e32 v3, v32, v72
	v_cvt_pk_bf16_f32 v3, v3, s0
	global_store_short v[6:7], v3, off offset:128
	v_mul_f32_e32 v3, v45, v72
	v_cvt_pk_bf16_f32 v3, v3, s0
	global_store_short v[6:7], v3, off offset:192
	v_add_u32_e32 v6, 11, v2
	v_ashrrev_i32_e32 v7, 31, v6
	v_lshlrev_b64 v[6:7], 11, v[6:7]
	v_mul_f32_e32 v3, v41, v81
	v_lshl_add_u64 v[6:7], v[4:5], 0, v[6:7]
	v_cvt_pk_bf16_f32 v3, v3, s0
	global_store_short v[6:7], v3, off
	v_mul_f32_e32 v3, v38, v81
	v_cvt_pk_bf16_f32 v3, v3, s0
	global_store_short v[6:7], v3, off offset:64
	v_mul_f32_e32 v3, v40, v81
	v_cvt_pk_bf16_f32 v3, v3, s0
	global_store_short v[6:7], v3, off offset:128
	v_mul_f32_e32 v3, v39, v81
	v_cvt_pk_bf16_f32 v3, v3, s0
; __device__ __forceinline__ void attn_unit(LAS unsigned char* lds, const bf16_t* Z, bf16_t* A2, const float* tabg, int seq_base, int S, int h, int qb, float lam) {
;     ...
; #pragma unroll
;         for (int r = 0; r < 16; ++r) { const int q = (r & 3) + 8 * (r >> 2) + 4 * hie;
;             bf16_t* orow = A2 + (size_t)(seq_base + qlo + q) * DM + h * 128 + r32e;
; #pragma unroll
;             for (int d = 0; d < 4; ++d) orow[d * 32] = (bf16_t)(pk2(O[d][r] * ss[r], 0.f) & 0xffffu); }
	global_store_short v[6:7], v3, off offset:192
	v_add_u32_e32 v6, 16, v2
	v_ashrrev_i32_e32 v7, 31, v6
	v_lshlrev_b64 v[6:7], 11, v[6:7]
	v_mul_f32_e32 v3, v37, v79
	v_lshl_add_u64 v[6:7], v[4:5], 0, v[6:7]
	v_cvt_pk_bf16_f32 v3, v3, s0
	global_store_short v[6:7], v3, off
	v_mul_f32_e32 v3, v42, v79
	v_cvt_pk_bf16_f32 v3, v3, s0
	global_store_short v[6:7], v3, off offset:64
	v_mul_f32_e32 v3, v43, v79
	v_cvt_pk_bf16_f32 v3, v3, s0
	global_store_short v[6:7], v3, off offset:128
	v_mul_f32_e32 v3, v44, v79
	v_cvt_pk_bf16_f32 v3, v3, s0
	global_store_short v[6:7], v3, off offset:192
	v_add_u32_e32 v6, 17, v2
	v_ashrrev_i32_e32 v7, 31, v6
	v_lshlrev_b64 v[6:7], 11, v[6:7]
	v_mul_f32_e32 v3, v36, v75
	v_lshl_add_u64 v[6:7], v[4:5], 0, v[6:7]
	v_cvt_pk_bf16_f32 v3, v3, s0
	global_store_short v[6:7], v3, off
	v_mul_f32_e32 v3, v34, v75
	v_cvt_pk_bf16_f32 v3, v3, s0
	global_store_short v[6:7], v3, off offset:64
	v_mul_f32_e32 v3, v35, v75
	v_cvt_pk_bf16_f32 v3, v3, s0
	global_store_short v[6:7], v3, off offset:128
	v_mul_f32_e32 v3, v33, v75
	v_cvt_pk_bf16_f32 v3, v3, s0
	global_store_short v[6:7], v3, off offset:192
	v_add_u32_e32 v6, 18, v2
	v_ashrrev_i32_e32 v7, 31, v6
	v_lshlrev_b64 v[6:7], 11, v[6:7]
	v_mul_f32_e32 v3, v51, v76
	v_lshl_add_u64 v[6:7], v[4:5], 0, v[6:7]
	v_cvt_pk_bf16_f32 v3, v3, s0
	global_store_short v[6:7], v3, off
	v_mul_f32_e32 v3, v50, v76
	v_cvt_pk_bf16_f32 v3, v3, s0
	global_store_short v[6:7], v3, off offset:64
	v_mul_f32_e32 v3, v52, v76
	v_cvt_pk_bf16_f32 v3, v3, s0
	global_store_short v[6:7], v3, off offset:128
	v_mul_f32_e32 v3, v53, v76
	v_cvt_pk_bf16_f32 v3, v3, s0
	global_store_short v[6:7], v3, off offset:192
	v_add_u32_e32 v6, 19, v2
	v_ashrrev_i32_e32 v7, 31, v6
	v_lshlrev_b64 v[6:7], 11, v[6:7]
	v_mul_f32_e32 v3, v49, v83
	v_lshl_add_u64 v[6:7], v[4:5], 0, v[6:7]
	v_cvt_pk_bf16_f32 v3, v3, s0
	global_store_short v[6:7], v3, off
	v_mul_f32_e32 v3, v47, v83
	v_cvt_pk_bf16_f32 v3, v3, s0
	global_store_short v[6:7], v3, off offset:64
	v_mul_f32_e32 v3, v48, v83
	v_cvt_pk_bf16_f32 v3, v3, s0
	global_store_short v[6:7], v3, off offset:128
	v_mul_f32_e32 v3, v46, v83
	v_cvt_pk_bf16_f32 v3, v3, s0
	global_store_short v[6:7], v3, off offset:192
	v_add_u32_e32 v6, 24, v2
	v_ashrrev_i32_e32 v7, 31, v6
	v_lshlrev_b64 v[6:7], 11, v[6:7]
	v_mul_f32_e32 v3, v59, v84
	v_lshl_add_u64 v[6:7], v[4:5], 0, v[6:7]
	v_cvt_pk_bf16_f32 v3, v3, s0
	global_store_short v[6:7], v3, off
	v_mul_f32_e32 v3, v58, v84
	v_cvt_pk_bf16_f32 v3, v3, s0
	global_store_short v[6:7], v3, off offset:64
	v_mul_f32_e32 v3, v60, v84
	v_cvt_pk_bf16_f32 v3, v3, s0
	global_store_short v[6:7], v3, off offset:128
	v_mul_f32_e32 v3, v61, v84
	v_cvt_pk_bf16_f32 v3, v3, s0
	global_store_short v[6:7], v3, off offset:192
	v_add_u32_e32 v6, 25, v2
	v_ashrrev_i32_e32 v7, 31, v6
	v_lshlrev_b64 v[6:7], 11, v[6:7]
	v_mul_f32_e32 v3, v57, v85
	v_lshl_add_u64 v[6:7], v[4:5], 0, v[6:7]
	v_cvt_pk_bf16_f32 v3, v3, s0
	global_store_short v[6:7], v3, off
	v_mul_f32_e32 v3, v55, v85
	v_cvt_pk_bf16_f32 v3, v3, s0
	global_store_short v[6:7], v3, off offset:64
	v_mul_f32_e32 v3, v56, v85
	v_cvt_pk_bf16_f32 v3, v3, s0
	global_store_short v[6:7], v3, off offset:128
	v_mul_f32_e32 v3, v54, v85
	v_cvt_pk_bf16_f32 v3, v3, s0
	global_store_short v[6:7], v3, off offset:192
	v_add_u32_e32 v6, 26, v2
	v_ashrrev_i32_e32 v7, 31, v6
	v_lshlrev_b64 v[6:7], 11, v[6:7]
	v_mul_f32_e32 v3, v62, v86
	v_lshl_add_u64 v[6:7], v[4:5], 0, v[6:7]
	v_cvt_pk_bf16_f32 v3, v3, s0
	global_store_short v[6:7], v3, off
	v_mul_f32_e32 v3, v63, v86
	v_cvt_pk_bf16_f32 v3, v3, s0
	global_store_short v[6:7], v3, off offset:64
	v_mul_f32_e32 v3, v64, v86
	v_cvt_pk_bf16_f32 v3, v3, s0
	global_store_short v[6:7], v3, off offset:128
	v_mul_f32_e32 v3, v69, v86
	v_cvt_pk_bf16_f32 v3, v3, s0
	v_add_u32_e32 v2, 27, v2
	global_store_short v[6:7], v3, off offset:192
	v_ashrrev_i32_e32 v3, 31, v2
	v_lshlrev_b64 v[2:3], 11, v[2:3]
	v_lshl_add_u64 v[2:3], v[4:5], 0, v[2:3]
	v_mul_f32_e32 v4, v68, v87
	v_cvt_pk_bf16_f32 v4, v4, s0
	global_store_short v[2:3], v4, off
	v_mul_f32_e32 v4, v66, v87
	v_cvt_pk_bf16_f32 v4, v4, s0
	global_store_short v[2:3], v4, off offset:64
	v_mul_f32_e32 v4, v67, v87
	v_cvt_pk_bf16_f32 v4, v4, s0
	global_store_short v[2:3], v4, off offset:128
	v_mul_f32_e32 v4, v65, v87
	v_cvt_pk_bf16_f32 v4, v4, s0
	global_store_short v[2:3], v4, off offset:192
	s_branch .LBB0_281
